# layer-0 merge phase: layer-1 w_up/w_down conversions moved off the 32 early-table blocks onto blocks 160-255
# baseline (speedup 1.0000x reference)
.LBB0_410:
	v_readlane_b32 s12, v255, 22
	s_cmpk_gt_i32 s12, 0x7f
	v_readlane_b32 s2, v255, 47
	s_cselect_b64 s[0:1], -1, 0
	v_readlane_b32 s3, v255, 48
	s_and_b64 s[0:1], s[2:3], s[0:1]
	s_and_b64 s[2:3], s[48:49], s[0:1]
	s_cmpk_lt_i32 s12, 0x290
	v_readlane_b32 s0, v255, 18
	s_cselect_b64 s[6:7], -1, 0
	v_readlane_b32 s1, v255, 19
	s_add_u32 s0, s0, 0xb00000
	s_addc_u32 s1, s1, 0
	s_add_u32 s8, s72, 0x12558000
	s_addc_u32 s9, s73, 0
	v_readlane_b32 s10, v255, 16
	v_readlane_b32 s11, v255, 17
	s_add_u32 s18, s10, 0x1600000
	s_addc_u32 s19, s11, 0
	s_add_u32 s40, s72, 0x11a58000
	s_addc_u32 s41, s73, 0
	s_and_b64 s[2:3], s[2:3], s[6:7]
	s_andn2_b64 vcc, exec, s[2:3]
	s_movk_i32 s83, 0x2000
	s_movk_i32 s86, 0x1fff
	s_mov_b32 s70, 0x800000
	v_readlane_b32 s89, v255, 44
	v_readlane_b32 s13, v255, 23
	s_cbranch_vccnz .LBB0_432
	s_cmpk_lt_i32 s12, 0xa0
	s_cbranch_scc1 .LBB0_432
	s_add_i32 s7, s12, 0x180
	s_and_b32 s5, s12, 15
	s_and_b32 s6, s12, 7
	s_lshr_b32 s10, s7, 4
	s_branch .LBB0_414

.LBB0_413:
	v_mov_b32_e32 v7, v166
	s_lshl_b32 s28, s13, 8
	s_lshl_b32 s12, s11, 6
	s_lshl_b64 s[16:17], s[28:29], 2
	v_ashrrev_i32_e32 v8, 8, v7
	s_add_u32 s16, s54, s16
	v_lshlrev_b32_e32 v0, 2, v7
	v_add_u32_e32 v4, s12, v8
	s_addc_u32 s17, s55, s17
	v_and_b32_e32 v0, 0x3fc, v0
	v_ashrrev_i32_e32 v5, 31, v4
	v_lshl_add_u64 v[2:3], s[16:17], 0, v[0:1]
	v_mul_lo_u32 v6, s52, v5
	v_mul_lo_u32 v9, s53, v4
	v_mad_u64_u32 v[4:5], s[16:17], s52, v4, 0
	v_add3_u32 v5, v5, v6, v9
	v_add_u32_e32 v6, 0x200, v7
	v_lshl_add_u64 v[4:5], v[4:5], 2, v[2:3]
	v_ashrrev_i32_e32 v10, 8, v6
	s_waitcnt vmcnt(0)
	s_barrier
	global_load_dword v9, v[4:5], off
	v_add_u32_e32 v4, s12, v10
	v_ashrrev_i32_e32 v5, 31, v4
	v_mul_lo_u32 v11, s52, v5
	v_mul_lo_u32 v12, s53, v4
	v_mad_u64_u32 v[4:5], s[16:17], s52, v4, 0
	v_add3_u32 v5, v5, v11, v12
	v_lshl_add_u64 v[4:5], v[4:5], 2, v[2:3]
	global_load_dword v11, v[4:5], off
	v_add_u32_e32 v5, 0x400, v7
	v_ashrrev_i32_e32 v12, 8, v5
	v_add_u32_e32 v4, s12, v12
	v_ashrrev_i32_e32 v13, 31, v4
	v_mul_lo_u32 v13, s52, v13
	v_mul_lo_u32 v16, s53, v4
	v_mad_u64_u32 v[14:15], s[16:17], s52, v4, 0
	v_add3_u32 v15, v15, v13, v16
	v_lshl_add_u64 v[14:15], v[14:15], 2, v[2:3]
	v_add_u32_e32 v4, 0x600, v7
	global_load_dword v13, v[14:15], off
	v_ashrrev_i32_e32 v14, 8, v4
	v_add_u32_e32 v15, s12, v14
	v_ashrrev_i32_e32 v16, 31, v15
	v_mul_lo_u32 v18, s52, v16
	v_mul_lo_u32 v19, s53, v15
	v_mad_u64_u32 v[16:17], s[16:17], s52, v15, 0
	v_add3_u32 v17, v17, v18, v19
	v_lshl_add_u64 v[16:17], v[16:17], 2, v[2:3]
	global_load_dword v15, v[16:17], off
	v_add_u32_e32 v16, 0x800, v7
	v_ashrrev_i32_e32 v18, 8, v16
	v_add_u32_e32 v16, s12, v18
	v_ashrrev_i32_e32 v17, 31, v16
	v_mul_lo_u32 v19, s52, v17
	v_mul_lo_u32 v20, s53, v16
	v_mad_u64_u32 v[16:17], s[16:17], s52, v16, 0
	v_add3_u32 v17, v17, v19, v20
	v_lshl_add_u64 v[16:17], v[16:17], 2, v[2:3]
	global_load_dword v19, v[16:17], off
	v_add_u32_e32 v16, 0xa00, v7
	v_ashrrev_i32_e32 v20, 8, v16
	v_add_u32_e32 v16, s12, v20
	v_ashrrev_i32_e32 v17, 31, v16
	v_mul_lo_u32 v21, s52, v17
	v_mul_lo_u32 v22, s53, v16
	v_mad_u64_u32 v[16:17], s[16:17], s52, v16, 0
	v_add3_u32 v17, v17, v21, v22
	v_lshl_add_u64 v[16:17], v[16:17], 2, v[2:3]
	global_load_dword v21, v[16:17], off
	v_add_u32_e32 v16, 0xc00, v7
	v_ashrrev_i32_e32 v22, 8, v16
	v_add_u32_e32 v16, s12, v22
	v_ashrrev_i32_e32 v17, 31, v16
	v_mul_lo_u32 v23, s52, v17
	v_mul_lo_u32 v24, s53, v16
	v_mad_u64_u32 v[16:17], s[16:17], s52, v16, 0
	v_add3_u32 v17, v17, v23, v24
	v_lshl_add_u64 v[16:17], v[16:17], 2, v[2:3]
	global_load_dword v23, v[16:17], off
	v_add_u32_e32 v16, 0xe00, v7
	v_ashrrev_i32_e32 v24, 8, v16
	v_add_u32_e32 v16, s12, v24
	v_ashrrev_i32_e32 v17, 31, v16
	v_mul_lo_u32 v25, s52, v17
	v_mul_lo_u32 v26, s53, v16
	v_mad_u64_u32 v[16:17], s[16:17], s52, v16, 0
	v_add3_u32 v17, v17, v25, v26
	v_lshl_add_u64 v[16:17], v[16:17], 2, v[2:3]
	global_load_dword v25, v[16:17], off
	v_add_u32_e32 v16, 0x1000, v7
	v_ashrrev_i32_e32 v26, 8, v16
	v_add_u32_e32 v16, s12, v26
	v_ashrrev_i32_e32 v17, 31, v16
	v_mul_lo_u32 v27, s52, v17
	v_mul_lo_u32 v28, s53, v16
	v_mad_u64_u32 v[16:17], s[16:17], s52, v16, 0
	v_add3_u32 v17, v17, v27, v28
	v_lshl_add_u64 v[16:17], v[16:17], 2, v[2:3]
	global_load_dword v27, v[16:17], off
	v_add_u32_e32 v16, 0x1200, v7
	v_ashrrev_i32_e32 v28, 8, v16
	v_add_u32_e32 v16, s12, v28
	v_ashrrev_i32_e32 v17, 31, v16
	v_mul_lo_u32 v29, s52, v17
	v_mul_lo_u32 v30, s53, v16
	v_mad_u64_u32 v[16:17], s[16:17], s52, v16, 0
	v_add3_u32 v17, v17, v29, v30
	v_lshl_add_u64 v[16:17], v[16:17], 2, v[2:3]
	global_load_dword v29, v[16:17], off
	v_add_u32_e32 v16, 0x1400, v7
	v_ashrrev_i32_e32 v30, 8, v16
	v_add_u32_e32 v16, s12, v30
	v_ashrrev_i32_e32 v17, 31, v16
	v_mul_lo_u32 v31, s52, v17
	v_mul_lo_u32 v32, s53, v16
	v_mad_u64_u32 v[16:17], s[16:17], s52, v16, 0
	v_add3_u32 v17, v17, v31, v32
	v_lshl_add_u64 v[16:17], v[16:17], 2, v[2:3]
	global_load_dword v31, v[16:17], off
	v_add_u32_e32 v16, 0x1600, v7
	v_ashrrev_i32_e32 v32, 8, v16
	v_add_u32_e32 v16, s12, v32
	v_ashrrev_i32_e32 v17, 31, v16
	v_mul_lo_u32 v33, s52, v17
	v_mul_lo_u32 v34, s53, v16
	v_mad_u64_u32 v[16:17], s[16:17], s52, v16, 0
	v_add3_u32 v17, v17, v33, v34
	v_lshl_add_u64 v[16:17], v[16:17], 2, v[2:3]
	global_load_dword v33, v[16:17], off
	v_add_u32_e32 v16, 0x1800, v7
	v_ashrrev_i32_e32 v34, 8, v16
	v_add_u32_e32 v16, s12, v34
	v_ashrrev_i32_e32 v17, 31, v16
	v_mul_lo_u32 v35, s52, v17
	v_mul_lo_u32 v36, s53, v16
	v_mad_u64_u32 v[16:17], s[16:17], s52, v16, 0
	v_add3_u32 v17, v17, v35, v36
	v_lshl_add_u64 v[16:17], v[16:17], 2, v[2:3]
	global_load_dword v35, v[16:17], off
	v_add_u32_e32 v16, 0x1a00, v7
	v_ashrrev_i32_e32 v36, 8, v16
	v_add_u32_e32 v16, s12, v36
	v_ashrrev_i32_e32 v17, 31, v16
	v_mul_lo_u32 v37, s52, v17
	v_mul_lo_u32 v38, s53, v16
	v_mad_u64_u32 v[16:17], s[16:17], s52, v16, 0
	v_add3_u32 v17, v17, v37, v38
	v_lshl_add_u64 v[16:17], v[16:17], 2, v[2:3]
	global_load_dword v37, v[16:17], off
	v_add_u32_e32 v16, 0x1c00, v7
	v_ashrrev_i32_e32 v38, 8, v16
	v_add_u32_e32 v16, s12, v38
	v_ashrrev_i32_e32 v17, 31, v16
	v_mul_lo_u32 v39, s52, v17
	v_mul_lo_u32 v40, s53, v16
	v_mad_u64_u32 v[16:17], s[16:17], s52, v16, 0
	v_add3_u32 v17, v17, v39, v40
	v_lshl_add_u64 v[16:17], v[16:17], 2, v[2:3]
	global_load_dword v39, v[16:17], off
	v_add_u32_e32 v16, 0x1e00, v7
	v_ashrrev_i32_e32 v40, 8, v16
	v_add_u32_e32 v16, s12, v40
	v_ashrrev_i32_e32 v17, 31, v16
	v_mul_lo_u32 v41, s52, v17
	v_mul_lo_u32 v42, s53, v16
	v_mad_u64_u32 v[16:17], s[16:17], s52, v16, 0
	v_add3_u32 v17, v17, v41, v42
	v_lshl_add_u64 v[16:17], v[16:17], 2, v[2:3]
	global_load_dword v41, v[16:17], off
	v_add_u32_e32 v16, 0x2000, v7
	v_ashrrev_i32_e32 v42, 8, v16
	v_add_u32_e32 v16, s12, v42
	v_ashrrev_i32_e32 v17, 31, v16
	v_mul_lo_u32 v43, s52, v17
	v_mul_lo_u32 v44, s53, v16
	v_mad_u64_u32 v[16:17], s[16:17], s52, v16, 0
	v_add3_u32 v17, v17, v43, v44
	v_lshl_add_u64 v[16:17], v[16:17], 2, v[2:3]
	global_load_dword v43, v[16:17], off
	v_add_u32_e32 v16, 0x2200, v7
	v_ashrrev_i32_e32 v44, 8, v16
	v_add_u32_e32 v16, s12, v44
	v_ashrrev_i32_e32 v17, 31, v16
	v_mul_lo_u32 v45, s52, v17
	v_mul_lo_u32 v46, s53, v16
	v_mad_u64_u32 v[16:17], s[16:17], s52, v16, 0
	v_add3_u32 v17, v17, v45, v46
	v_lshl_add_u64 v[16:17], v[16:17], 2, v[2:3]
	global_load_dword v45, v[16:17], off
	v_add_u32_e32 v16, 0x2400, v7
	v_ashrrev_i32_e32 v46, 8, v16
	v_add_u32_e32 v16, s12, v46
	v_ashrrev_i32_e32 v17, 31, v16
	v_mul_lo_u32 v47, s52, v17
	v_mul_lo_u32 v48, s53, v16
	v_mad_u64_u32 v[16:17], s[16:17], s52, v16, 0
	v_add3_u32 v17, v17, v47, v48
	v_lshl_add_u64 v[16:17], v[16:17], 2, v[2:3]
	global_load_dword v47, v[16:17], off
	v_add_u32_e32 v16, 0x2600, v7
	v_ashrrev_i32_e32 v48, 8, v16
	v_add_u32_e32 v16, s12, v48
	v_ashrrev_i32_e32 v17, 31, v16
	v_mul_lo_u32 v49, s52, v17
	v_mul_lo_u32 v50, s53, v16
	v_mad_u64_u32 v[16:17], s[16:17], s52, v16, 0
	v_add3_u32 v17, v17, v49, v50
	v_lshl_add_u64 v[16:17], v[16:17], 2, v[2:3]
	global_load_dword v49, v[16:17], off
	v_add_u32_e32 v16, 0x2800, v7
	v_ashrrev_i32_e32 v50, 8, v16
	v_add_u32_e32 v16, s12, v50
	v_ashrrev_i32_e32 v17, 31, v16
	v_mul_lo_u32 v51, s52, v17
	v_mul_lo_u32 v52, s53, v16
	v_mad_u64_u32 v[16:17], s[16:17], s52, v16, 0
	v_add3_u32 v17, v17, v51, v52
	v_lshl_add_u64 v[16:17], v[16:17], 2, v[2:3]
	global_load_dword v51, v[16:17], off
	v_add_u32_e32 v16, 0x2a00, v7
	v_ashrrev_i32_e32 v52, 8, v16
	v_add_u32_e32 v16, s12, v52
	v_ashrrev_i32_e32 v17, 31, v16
	v_mul_lo_u32 v53, s52, v17
	v_mul_lo_u32 v54, s53, v16
	v_mad_u64_u32 v[16:17], s[16:17], s52, v16, 0
	v_add3_u32 v17, v17, v53, v54
	v_lshl_add_u64 v[16:17], v[16:17], 2, v[2:3]
	global_load_dword v53, v[16:17], off
	v_add_u32_e32 v16, 0x2c00, v7
	v_ashrrev_i32_e32 v54, 8, v16
	v_add_u32_e32 v16, s12, v54
	v_ashrrev_i32_e32 v17, 31, v16
	v_mul_lo_u32 v55, s52, v17
	v_mul_lo_u32 v56, s53, v16
	v_mad_u64_u32 v[16:17], s[16:17], s52, v16, 0
	v_add3_u32 v17, v17, v55, v56
	v_lshl_add_u64 v[16:17], v[16:17], 2, v[2:3]
	global_load_dword v55, v[16:17], off
	v_add_u32_e32 v16, 0x2e00, v7
	v_ashrrev_i32_e32 v56, 8, v16
	v_add_u32_e32 v16, s12, v56
	v_ashrrev_i32_e32 v17, 31, v16
	v_mul_lo_u32 v57, s52, v17
	v_mul_lo_u32 v58, s53, v16
	v_mad_u64_u32 v[16:17], s[16:17], s52, v16, 0
	v_add3_u32 v17, v17, v57, v58
	v_lshl_add_u64 v[16:17], v[16:17], 2, v[2:3]
	global_load_dword v57, v[16:17], off
	v_add_u32_e32 v16, 0x3000, v7
	v_ashrrev_i32_e32 v58, 8, v16
	v_add_u32_e32 v16, s12, v58
	v_ashrrev_i32_e32 v17, 31, v16
	v_mul_lo_u32 v59, s52, v17
	v_mul_lo_u32 v60, s53, v16
	v_mad_u64_u32 v[16:17], s[16:17], s52, v16, 0
	v_add3_u32 v17, v17, v59, v60
	v_lshl_add_u64 v[16:17], v[16:17], 2, v[2:3]
	global_load_dword v59, v[16:17], off
	v_add_u32_e32 v16, 0x3200, v7
	v_ashrrev_i32_e32 v60, 8, v16
	v_add_u32_e32 v16, s12, v60
	v_ashrrev_i32_e32 v17, 31, v16
	v_mul_lo_u32 v61, s52, v17
	v_mul_lo_u32 v62, s53, v16
	v_mad_u64_u32 v[16:17], s[16:17], s52, v16, 0
	v_add3_u32 v17, v17, v61, v62
	v_lshl_add_u64 v[16:17], v[16:17], 2, v[2:3]
	global_load_dword v61, v[16:17], off
	v_add_u32_e32 v16, 0x3400, v7
	v_ashrrev_i32_e32 v62, 8, v16
	v_add_u32_e32 v16, s12, v62
	v_ashrrev_i32_e32 v17, 31, v16
	v_mul_lo_u32 v63, s52, v17
	v_mul_lo_u32 v64, s53, v16
	v_mad_u64_u32 v[16:17], s[16:17], s52, v16, 0
	v_add3_u32 v17, v17, v63, v64
	v_lshl_add_u64 v[16:17], v[16:17], 2, v[2:3]
	global_load_dword v63, v[16:17], off
	v_add_u32_e32 v16, 0x3600, v7
	v_ashrrev_i32_e32 v64, 8, v16
	v_add_u32_e32 v16, s12, v64
	v_ashrrev_i32_e32 v17, 31, v16
	v_mul_lo_u32 v65, s52, v17
	v_mul_lo_u32 v66, s53, v16
	v_mad_u64_u32 v[16:17], s[16:17], s52, v16, 0
	v_add3_u32 v17, v17, v65, v66
	v_lshl_add_u64 v[16:17], v[16:17], 2, v[2:3]
	global_load_dword v65, v[16:17], off
	v_add_u32_e32 v16, 0x3800, v7
	v_ashrrev_i32_e32 v66, 8, v16
	v_add_u32_e32 v16, s12, v66
	v_ashrrev_i32_e32 v17, 31, v16
	v_mul_lo_u32 v67, s52, v17
	v_mul_lo_u32 v68, s53, v16
	v_mad_u64_u32 v[16:17], s[16:17], s52, v16, 0
	v_add3_u32 v17, v17, v67, v68
	v_lshl_add_u64 v[16:17], v[16:17], 2, v[2:3]
	global_load_dword v67, v[16:17], off
	v_add_u32_e32 v16, 0x3a00, v7
	v_ashrrev_i32_e32 v68, 8, v16
	v_add_u32_e32 v16, s12, v68
	v_ashrrev_i32_e32 v17, 31, v16
	v_mul_lo_u32 v69, s52, v17
	v_mul_lo_u32 v70, s53, v16
	v_mad_u64_u32 v[16:17], s[16:17], s52, v16, 0
	v_add3_u32 v17, v17, v69, v70
	v_lshl_add_u64 v[16:17], v[16:17], 2, v[2:3]
	global_load_dword v69, v[16:17], off
	v_add_u32_e32 v16, 0x3c00, v7
	v_ashrrev_i32_e32 v70, 8, v16
	v_add_u32_e32 v16, s12, v70
	v_ashrrev_i32_e32 v17, 31, v16
	v_mul_lo_u32 v71, s52, v17
	v_mul_lo_u32 v72, s53, v16
	v_mad_u64_u32 v[16:17], s[16:17], s52, v16, 0
	v_add3_u32 v17, v17, v71, v72
	v_lshl_add_u64 v[16:17], v[16:17], 2, v[2:3]
	global_load_dword v71, v[16:17], off
	v_add_u32_e32 v16, 0x3e00, v7
	v_ashrrev_i32_e32 v72, 8, v16
	v_add_u32_e32 v16, s12, v72
	v_ashrrev_i32_e32 v17, 31, v16
	v_mul_lo_u32 v73, s52, v17
	v_mul_lo_u32 v74, s53, v16
	v_mad_u64_u32 v[16:17], s[12:13], s52, v16, 0
	v_add3_u32 v17, v17, v73, v74
	v_lshl_add_u64 v[2:3], v[16:17], 2, v[2:3]
	global_load_dword v2, v[2:3], off
	v_add_u32_e32 v0, 0, v0
	v_mad_i32_i24 v3, v8, s75, v0
	s_waitcnt vmcnt(31)
	ds_write_b32 v3, v9
	v_mad_i32_i24 v3, v10, s75, v0
	s_waitcnt vmcnt(30)
	ds_write_b32 v3, v11
	v_mad_i32_i24 v3, v12, s75, v0
	s_waitcnt vmcnt(29)
	ds_write_b32 v3, v13
	v_mad_i32_i24 v3, v14, s75, v0
	s_waitcnt vmcnt(28)
	ds_write_b32 v3, v15
	v_mad_i32_i24 v3, v18, s75, v0
	s_waitcnt vmcnt(27)
	ds_write_b32 v3, v19
	v_mad_i32_i24 v3, v20, s75, v0
	s_waitcnt vmcnt(26)
	ds_write_b32 v3, v21
	v_mad_i32_i24 v3, v22, s75, v0
	s_waitcnt vmcnt(25)
	ds_write_b32 v3, v23
	v_mad_i32_i24 v3, v24, s75, v0
	s_waitcnt vmcnt(24)
	ds_write_b32 v3, v25
	v_mad_i32_i24 v3, v26, s75, v0
	s_waitcnt vmcnt(23)
	ds_write_b32 v3, v27
	v_mad_i32_i24 v3, v28, s75, v0
	s_waitcnt vmcnt(22)
	ds_write_b32 v3, v29
	v_mad_i32_i24 v3, v30, s75, v0
	s_waitcnt vmcnt(21)
	ds_write_b32 v3, v31
	v_mad_i32_i24 v3, v32, s75, v0
	s_waitcnt vmcnt(20)
	ds_write_b32 v3, v33
	v_mad_i32_i24 v3, v34, s75, v0
	s_waitcnt vmcnt(19)
	ds_write_b32 v3, v35
	v_mad_i32_i24 v3, v36, s75, v0
	s_waitcnt vmcnt(18)
	ds_write_b32 v3, v37
	v_mad_i32_i24 v3, v38, s75, v0
	s_waitcnt vmcnt(17)
	ds_write_b32 v3, v39
	v_mad_i32_i24 v3, v40, s75, v0
	s_waitcnt vmcnt(16)
	ds_write_b32 v3, v41
	v_mad_i32_i24 v3, v42, s75, v0
	s_waitcnt vmcnt(15)
	ds_write_b32 v3, v43
	v_mad_i32_i24 v3, v44, s75, v0
	s_waitcnt vmcnt(14)
	ds_write_b32 v3, v45
	v_mad_i32_i24 v3, v46, s75, v0
	s_waitcnt vmcnt(13)
	ds_write_b32 v3, v47
	v_mad_i32_i24 v3, v48, s75, v0
	s_waitcnt vmcnt(12)
	ds_write_b32 v3, v49
	v_mad_i32_i24 v3, v50, s75, v0
	s_waitcnt vmcnt(11)
	ds_write_b32 v3, v51
	v_mad_i32_i24 v3, v52, s75, v0
	s_waitcnt vmcnt(10)
	ds_write_b32 v3, v53
	v_mad_i32_i24 v3, v54, s75, v0
	s_waitcnt vmcnt(9)
	ds_write_b32 v3, v55
	v_mad_i32_i24 v3, v56, s75, v0
	s_waitcnt vmcnt(8)
	ds_write_b32 v3, v57
	v_mad_i32_i24 v3, v58, s75, v0
	s_waitcnt vmcnt(7)
	ds_write_b32 v3, v59
	v_mad_i32_i24 v3, v60, s75, v0
	s_waitcnt vmcnt(6)
	ds_write_b32 v3, v61
	v_mad_i32_i24 v3, v62, s75, v0
	s_waitcnt vmcnt(5)
	ds_write_b32 v3, v63
	v_mad_i32_i24 v3, v64, s75, v0
	s_waitcnt vmcnt(4)
	ds_write_b32 v3, v65
	v_mad_i32_i24 v3, v66, s75, v0
	s_waitcnt vmcnt(3)
	ds_write_b32 v3, v67
	v_mad_i32_i24 v3, v68, s75, v0
	s_waitcnt vmcnt(2)
	ds_write_b32 v3, v69
	v_mad_i32_i24 v3, v70, s75, v0
	v_mad_i32_i24 v0, v72, s75, v0
	s_lshl_b32 s11, s11, 7
	s_add_u32 s12, s42, s11
	s_addc_u32 s13, s43, 0
	s_add_i32 s10, s10, 8
	s_waitcnt vmcnt(1)
	ds_write_b32 v3, v71
	s_waitcnt vmcnt(0)
	ds_write_b32 v0, v2
	v_lshlrev_b32_e32 v0, 3, v7
	v_and_b32_e32 v0, 56, v0
	v_mad_u32_u24 v14, v0, s75, 0
	v_lshlrev_b32_e32 v0, 1, v0
	v_lshl_add_u64 v[12:13], s[12:13], 0, v[0:1]
	v_ashrrev_i32_e32 v0, 3, v7
	v_lshl_add_u32 v2, v0, 2, v14
	s_waitcnt lgkmcnt(0)
	s_barrier
	ds_read_b32 v3, v2
	ds_read_b32 v7, v2 offset:1028
	v_add_u32_e32 v0, s28, v0
	v_mul_lo_u32 v15, s3, v0
	s_waitcnt lgkmcnt(0)
	v_cvt_pk_bf16_f32 v8, v3, v7
	ds_read_b32 v3, v2 offset:2056
	ds_read_b32 v7, v2 offset:3084
	s_waitcnt lgkmcnt(0)
	v_cvt_pk_bf16_f32 v9, v3, v7
	ds_read_b32 v3, v2 offset:4112
	ds_read_b32 v7, v2 offset:5140
	s_waitcnt lgkmcnt(0)
	v_cvt_pk_bf16_f32 v10, v3, v7
	ds_read_b32 v3, v2 offset:6168
	ds_read_b32 v2, v2 offset:7196
	s_waitcnt lgkmcnt(0)
	v_cvt_pk_bf16_f32 v11, v3, v2
	v_ashrrev_i32_e32 v2, 31, v0
	v_mul_lo_u32 v7, s2, v2
	v_mad_u64_u32 v[2:3], s[12:13], s2, v0, 0
	v_add3_u32 v3, v3, v7, v15
	v_lshl_add_u64 v[2:3], v[2:3], 1, v[12:13]
	v_ashrrev_i32_e32 v0, 3, v6
	global_store_dwordx4 v[2:3], v[8:11], off
	v_lshl_add_u32 v2, v0, 2, v14
	ds_read_b32 v3, v2
	ds_read_b32 v6, v2 offset:1028
	v_add_u32_e32 v0, s28, v0
	v_mul_lo_u32 v11, s3, v0
	s_waitcnt lgkmcnt(0)
	v_cvt_pk_bf16_f32 v6, v3, v6
	ds_read_b32 v3, v2 offset:2056
	ds_read_b32 v7, v2 offset:3084
	s_waitcnt lgkmcnt(0)
	v_cvt_pk_bf16_f32 v7, v3, v7
	ds_read_b32 v3, v2 offset:4112
	ds_read_b32 v8, v2 offset:5140
	s_waitcnt lgkmcnt(0)
	v_cvt_pk_bf16_f32 v8, v3, v8
	ds_read_b32 v3, v2 offset:6168
	ds_read_b32 v2, v2 offset:7196
	s_waitcnt lgkmcnt(0)
	v_cvt_pk_bf16_f32 v9, v3, v2
	v_ashrrev_i32_e32 v2, 31, v0
	v_mul_lo_u32 v10, s2, v2
	v_mad_u64_u32 v[2:3], s[12:13], s2, v0, 0
	v_add3_u32 v3, v3, v10, v11
	v_lshl_add_u64 v[2:3], v[2:3], 1, v[12:13]
	v_ashrrev_i32_e32 v0, 3, v5
	global_store_dwordx4 v[2:3], v[6:9], off
	v_lshl_add_u32 v2, v0, 2, v14
	ds_read_b32 v3, v2
	ds_read_b32 v5, v2 offset:1028
	v_add_u32_e32 v0, s28, v0
	v_mul_lo_u32 v10, s3, v0
	s_waitcnt lgkmcnt(0)
	v_cvt_pk_bf16_f32 v6, v3, v5
	ds_read_b32 v3, v2 offset:2056
	ds_read_b32 v5, v2 offset:3084
	s_waitcnt lgkmcnt(0)
	v_cvt_pk_bf16_f32 v7, v3, v5
	ds_read_b32 v3, v2 offset:4112
	ds_read_b32 v5, v2 offset:5140
	s_waitcnt lgkmcnt(0)
	v_cvt_pk_bf16_f32 v8, v3, v5
	ds_read_b32 v3, v2 offset:6168
	ds_read_b32 v2, v2 offset:7196
	s_waitcnt lgkmcnt(0)
	v_cvt_pk_bf16_f32 v9, v3, v2
	v_ashrrev_i32_e32 v2, 31, v0
	v_mul_lo_u32 v5, s2, v2
	v_mad_u64_u32 v[2:3], s[12:13], s2, v0, 0
	v_add3_u32 v3, v3, v5, v10
	v_lshl_add_u64 v[2:3], v[2:3], 1, v[12:13]
	v_ashrrev_i32_e32 v0, 3, v4
	global_store_dwordx4 v[2:3], v[6:9], off
	v_lshl_add_u32 v5, v0, 2, v14
	ds_read_b32 v2, v5
	ds_read_b32 v3, v5 offset:1028
	v_add_u32_e32 v0, s28, v0
	v_mul_lo_u32 v9, s3, v0
	s_waitcnt lgkmcnt(0)
	v_cvt_pk_bf16_f32 v2, v2, v3
	ds_read_b32 v3, v5 offset:2056
	ds_read_b32 v4, v5 offset:3084
	s_waitcnt lgkmcnt(0)
	v_cvt_pk_bf16_f32 v3, v3, v4
	ds_read_b32 v4, v5 offset:4112
	ds_read_b32 v6, v5 offset:5140
	s_waitcnt lgkmcnt(0)
	v_cvt_pk_bf16_f32 v4, v4, v6
	ds_read_b32 v6, v5 offset:6168
	ds_read_b32 v5, v5 offset:7196
	s_waitcnt lgkmcnt(0)
	v_cvt_pk_bf16_f32 v5, v6, v5
	v_ashrrev_i32_e32 v6, 31, v0
	v_mul_lo_u32 v8, s2, v6
	v_mad_u64_u32 v[6:7], s[2:3], s2, v0, 0
	v_add3_u32 v7, v7, v8, v9
	s_add_i32 s2, s7, 0x60
	v_lshl_add_u64 v[6:7], v[6:7], 1, v[12:13]
	s_cmpk_lt_i32 s7, 0x3d0
	s_mov_b32 s7, s2
	global_store_dwordx4 v[6:7], v[2:5], off
	s_cbranch_scc0 .LBB0_431
